# scan: y output stored straight from the accumulators in stage Y by waves 4-7 (dwordx2 per lane); per-chunk LDS FLUSH read/convert/store removed from all waves
# baseline (speedup 1.0000x reference)
.LBB0_393:
	s_or_b64 exec, exec, s[74:75]
	s_lshl_b64 s[2:3], s[2:3], 24
	s_lshl_b64 s[2:3], s[2:3], 1
	v_readlane_b32 s19, v254, 44
	s_waitcnt lgkmcnt(0)
	s_barrier
	s_add_u32 s78, s19, s2
	v_readlane_b32 s2, v254, 45
	v_lshlrev_b32_e32 v189, 8, v18
	v_mov_b32_e32 v14, 0
	s_mov_b32 s20, 1
	s_addc_u32 s79, s2, s3
	s_mov_b32 s21, 0
	s_movk_i32 s19, 0x800
	v_add_u32_e32 v190, v152, v189
	s_mov_b32 s36, 0
	v_mov_b32_e32 v15, v14
	v_mov_b32_e32 v16, v14
	v_mov_b32_e32 v17, v14
	v_mov_b32_e32 v18, v14
	v_mov_b32_e32 v19, v14
	v_mov_b32_e32 v20, v14
	v_mov_b32_e32 v21, v14
	v_add_u32_e32 v241, v156, v163
	v_add_u32_e32 v200, v146, v145
	v_sub_u32_e32 v242, v164, v143
	v_mad_u32_u24 v242, v145, 5, v242
	v_add_u32_e32 v242, 0x18d00, v242
	v_mul_u32_u24_e32 v243, 5, v145
	v_sub_u32_e32 v243, v143, v243
	v_mul_i32_i24_e32 v243, 0x47, v243
	v_ashrrev_i32_e32 v243, 1, v243
	v_add_u32_e32 v243, v181, v243
	v_add_u32_e32 v192, v144, v145
	v_add_u32_e32 v199, v150, v145
	v_lshrrev_b32_e32 v244, 5, v198
	v_sub_u32_e32 v244, v184, v244
	v_and_b32_e32 v245, 15, v198
	v_sub_u32_e32 v246, 15, v245
	v_cndmask_b32_e64 v245, v246, v245, s[12:13]
	v_add_u32_e32 v244, v244, v245
	v_lshlrev_b32_e32 v244, 7, v244
	v_lshrrev_b32_e32 v245, 6, v198
	v_subrev_u32_e32 v245, 4, v245
	v_lshlrev_b32_e32 v245, 4, v245
	v_lshrrev_b32_e32 v246, 2, v145
	v_add_u32_e32 v245, v245, v246
	v_lshl_add_u32 v244, v245, 1, v244
	s_branch .LBB0_395

.LBB0_395:
.Lsx0_a:
.Lsx0_c:
	s_and_saveexec_b64 s[2:3], s[56:57]
	s_cbranch_execz .LBB0_403
	ds_read_b128 v[48:51], v174
	ds_read_b128 v[60:63], v192 offset:49152
	ds_read_b128 v[52:55], v174 offset:64
	ds_read_b128 v[64:67], v192 offset:49216
	ds_read_b128 v[56:59], v175
	ds_read_b128 v[68:71], v199
	ds_read_b128 v[72:75], v192 offset:58368
	ds_read_b128 v[76:79], v192 offset:58432
	ds_read_b128 v[80:83], v151
	ds_read_b128 v[84:87], v151 offset:16
	ds_read_b128 v[88:91], v151 offset:32
	ds_read_b128 v[92:95], v151 offset:48
	s_waitcnt lgkmcnt(10)
	v_mfma_f32_16x16x32_bf16 v[30:33], v[48:51], v[60:63], 0
	s_waitcnt lgkmcnt(8)
	v_mfma_f32_16x16x32_bf16 v[30:33], v[52:55], v[64:67], v[30:33]
	s_waitcnt lgkmcnt(6)
	v_mfma_f32_16x16x32_bf16 v[30:33], v[56:59], v[68:71], v[30:33]
	s_waitcnt lgkmcnt(5)
	v_mfma_f32_16x16x32_bf16 v[22:25], v[48:51], v[72:75], 0
	s_waitcnt lgkmcnt(4)
	v_mfma_f32_16x16x32_bf16 v[22:25], v[52:55], v[76:79], v[22:25]
	s_cmp_eq_u32 s36, 0
	s_cbranch_scc1 .Lis0b
	s_cmp_gt_u32 s36, 62
	s_cbranch_scc1 .Lis0b
	s_add_i32 s24, s19, 0xffffffc0
	s_add_i32 s25, s21, 0x30
	s_and_b64 s[98:99], s[12:13], exec
	s_cselect_b32 s24, s25, s24
	v_lshl_add_u32 v194, s24, 6, v183
	v_lshlrev_b32_e32 v112, 1, v194
	global_load_dword v5, v112, s[44:45]
	global_load_dword v207, v112, s[44:45] offset:-1024
	global_load_dword v6, v112, s[42:43]
	global_load_dword v208, v112, s[42:43] offset:-1024
	global_load_dword v7, v112, s[0:1]
	global_load_dword v209, v112, s[0:1] offset:-1024
	global_load_dword v8, v112, s[34:35]
	global_load_dword v210, v112, s[34:35] offset:-1024
	global_load_dword v9, v112, s[76:77]
	global_load_dword v211, v112, s[76:77] offset:-1024
	v_add_u32_e32 v194, s24, v184
	v_lshlrev_b32_e32 v114, 2, v194
	global_load_dword v110, v114, s[40:41]
	global_load_dword v212, v114, s[40:41] offset:-32
.Lis0b:
.Lsx0_d:
	s_setprio 3
	v_lshrrev_b32_e32 v96, 6, v198
	v_mul_u32_u24_e32 v96, 0x500, v96
	v_mad_u32_u24 v96, v145, 20, v96
	v_and_b32_e32 v97, 15, v198
	v_lshl_add_u32 v96, v97, 1, v96
	v_add_u32_e32 v96, 0x10a00, v96
	s_waitcnt lgkmcnt(0)
	s_nop 1
	v_fmac_f32_dpp v30, v30, v80 row_newbcast:0 row_mask:0xf bank_mask:0xf
	v_fmac_f32_dpp v31, v31, v80 row_newbcast:0 row_mask:0xf bank_mask:0xf
	v_fmac_f32_dpp v32, v32, v80 row_newbcast:0 row_mask:0xf bank_mask:0xf
	v_fmac_f32_dpp v33, v33, v80 row_newbcast:0 row_mask:0xf bank_mask:0xf
	v_fmac_f32_dpp v30, v30, v81 row_newbcast:1 row_mask:0xf bank_mask:0xf
	v_fmac_f32_dpp v31, v31, v81 row_newbcast:1 row_mask:0xf bank_mask:0xf
	v_fmac_f32_dpp v32, v32, v81 row_newbcast:1 row_mask:0xf bank_mask:0xf
	v_fmac_f32_dpp v33, v33, v81 row_newbcast:1 row_mask:0xf bank_mask:0xf
	v_fmac_f32_dpp v30, v30, v82 row_newbcast:2 row_mask:0xf bank_mask:0xf
	v_fmac_f32_dpp v31, v31, v82 row_newbcast:2 row_mask:0xf bank_mask:0xf
	v_fmac_f32_dpp v32, v32, v82 row_newbcast:2 row_mask:0xf bank_mask:0xf
	v_fmac_f32_dpp v33, v33, v82 row_newbcast:2 row_mask:0xf bank_mask:0xf
	v_fmac_f32_dpp v30, v30, v83 row_newbcast:3 row_mask:0xf bank_mask:0xf
	v_fmac_f32_dpp v31, v31, v83 row_newbcast:3 row_mask:0xf bank_mask:0xf
	v_fmac_f32_dpp v32, v32, v83 row_newbcast:3 row_mask:0xf bank_mask:0xf
	v_fmac_f32_dpp v33, v33, v83 row_newbcast:3 row_mask:0xf bank_mask:0xf
	v_fmac_f32_dpp v30, v30, v84 row_newbcast:4 row_mask:0xf bank_mask:0xf
	v_fmac_f32_dpp v31, v31, v84 row_newbcast:4 row_mask:0xf bank_mask:0xf
	v_fmac_f32_dpp v32, v32, v84 row_newbcast:4 row_mask:0xf bank_mask:0xf
	v_fmac_f32_dpp v33, v33, v84 row_newbcast:4 row_mask:0xf bank_mask:0xf
	v_fmac_f32_dpp v30, v30, v85 row_newbcast:5 row_mask:0xf bank_mask:0xf
	v_fmac_f32_dpp v31, v31, v85 row_newbcast:5 row_mask:0xf bank_mask:0xf
	v_fmac_f32_dpp v32, v32, v85 row_newbcast:5 row_mask:0xf bank_mask:0xf
	v_fmac_f32_dpp v33, v33, v85 row_newbcast:5 row_mask:0xf bank_mask:0xf
	v_fmac_f32_dpp v30, v30, v86 row_newbcast:6 row_mask:0xf bank_mask:0xf
	v_fmac_f32_dpp v31, v31, v86 row_newbcast:6 row_mask:0xf bank_mask:0xf
	v_fmac_f32_dpp v32, v32, v86 row_newbcast:6 row_mask:0xf bank_mask:0xf
	v_fmac_f32_dpp v33, v33, v86 row_newbcast:6 row_mask:0xf bank_mask:0xf
	v_fmac_f32_dpp v30, v30, v87 row_newbcast:7 row_mask:0xf bank_mask:0xf
	v_fmac_f32_dpp v31, v31, v87 row_newbcast:7 row_mask:0xf bank_mask:0xf
	v_fmac_f32_dpp v32, v32, v87 row_newbcast:7 row_mask:0xf bank_mask:0xf
	v_fmac_f32_dpp v33, v33, v87 row_newbcast:7 row_mask:0xf bank_mask:0xf
	v_fmac_f32_dpp v30, v30, v88 row_newbcast:8 row_mask:0xf bank_mask:0xf
	v_fmac_f32_dpp v31, v31, v88 row_newbcast:8 row_mask:0xf bank_mask:0xf
	v_fmac_f32_dpp v32, v32, v88 row_newbcast:8 row_mask:0xf bank_mask:0xf
	v_fmac_f32_dpp v33, v33, v88 row_newbcast:8 row_mask:0xf bank_mask:0xf
	v_fmac_f32_dpp v30, v30, v89 row_newbcast:9 row_mask:0xf bank_mask:0xf
	v_fmac_f32_dpp v31, v31, v89 row_newbcast:9 row_mask:0xf bank_mask:0xf
	v_fmac_f32_dpp v32, v32, v89 row_newbcast:9 row_mask:0xf bank_mask:0xf
	v_fmac_f32_dpp v33, v33, v89 row_newbcast:9 row_mask:0xf bank_mask:0xf
	v_fmac_f32_dpp v30, v30, v90 row_newbcast:10 row_mask:0xf bank_mask:0xf
	v_fmac_f32_dpp v31, v31, v90 row_newbcast:10 row_mask:0xf bank_mask:0xf
	v_fmac_f32_dpp v32, v32, v90 row_newbcast:10 row_mask:0xf bank_mask:0xf
	v_fmac_f32_dpp v33, v33, v90 row_newbcast:10 row_mask:0xf bank_mask:0xf
	v_fmac_f32_dpp v30, v30, v91 row_newbcast:11 row_mask:0xf bank_mask:0xf
	v_fmac_f32_dpp v31, v31, v91 row_newbcast:11 row_mask:0xf bank_mask:0xf
	v_fmac_f32_dpp v32, v32, v91 row_newbcast:11 row_mask:0xf bank_mask:0xf
	v_fmac_f32_dpp v33, v33, v91 row_newbcast:11 row_mask:0xf bank_mask:0xf
	v_fmac_f32_dpp v30, v30, v92 row_newbcast:12 row_mask:0xf bank_mask:0xf
	v_fmac_f32_dpp v31, v31, v92 row_newbcast:12 row_mask:0xf bank_mask:0xf
	v_fmac_f32_dpp v32, v32, v92 row_newbcast:12 row_mask:0xf bank_mask:0xf
	v_fmac_f32_dpp v33, v33, v92 row_newbcast:12 row_mask:0xf bank_mask:0xf
	v_fmac_f32_dpp v30, v30, v93 row_newbcast:13 row_mask:0xf bank_mask:0xf
	v_fmac_f32_dpp v31, v31, v93 row_newbcast:13 row_mask:0xf bank_mask:0xf
	v_fmac_f32_dpp v32, v32, v93 row_newbcast:13 row_mask:0xf bank_mask:0xf
	v_fmac_f32_dpp v33, v33, v93 row_newbcast:13 row_mask:0xf bank_mask:0xf
	v_fmac_f32_dpp v30, v30, v94 row_newbcast:14 row_mask:0xf bank_mask:0xf
	v_fmac_f32_dpp v31, v31, v94 row_newbcast:14 row_mask:0xf bank_mask:0xf
	v_fmac_f32_dpp v32, v32, v94 row_newbcast:14 row_mask:0xf bank_mask:0xf
	v_fmac_f32_dpp v33, v33, v94 row_newbcast:14 row_mask:0xf bank_mask:0xf
	v_cvt_pk_bf16_f32 v80, v30, v31
	v_cvt_pk_bf16_f32 v81, v32, v33
	ds_write_b16 v96, v80 offset:0
	ds_write_b16_d16_hi v96, v80 offset:80
	ds_write_b16 v96, v81 offset:160
	ds_write_b16_d16_hi v96, v81 offset:240
	s_setprio 1

.Lpq0_end:
	s_waitcnt lgkmcnt(0)
	s_barrier
	ds_read_b128 v[48:51], v180
	ds_read_b128 v[52:55], v241 offset:62976
	ds_read_b128 v[56:59], v241 offset:64256
	ds_read_b128 v[88:91], v242
	ds_read_b128 v[92:95], v242 offset:64
	s_and_b64 s[98:99], s[56:57], exec
	s_cbranch_scc0 .Lcp0
	s_cmp_gt_u32 s36, 62
	s_cbranch_scc1 .Lcp0
	s_cmp_eq_u32 s36, 0
	s_cbranch_scc1 .Lvw0
	s_waitcnt vmcnt(13)
	s_branch .Lvx0

.Lsy0_m2:
	s_or_b64 exec, exec, s[2:3]
	s_nop 7
	s_nop 1
	s_and_saveexec_b64 s[2:3], s[56:57]
	s_cbranch_execz .Lsy0_w1
	ds_write_b128 v179, v[22:25]
	s_add_i32 s98, s19, -16
	s_bitcmp1_b32 s12, 0
	s_cselect_b32 s98, s21, s98
	v_cvt_pk_bf16_f32 v246, v22, v23
	v_cvt_pk_bf16_f32 v247, v24, v25
	v_lshl_add_u32 v245, s98, 7, v244
	global_store_dwordx2 v245, v[246:247], s[78:79]

.LBB0_424:
.LBB0_426:
	s_add_i32 s24, s19, -16
	s_and_b64 s[2:3], s[12:13], exec
	s_waitcnt lgkmcnt(0)
	s_barrier
	s_cselect_b32 s2, s21, s24
	s_cmpk_lt_u32 s20, 0x7f
	s_cselect_b64 s[2:3], -1, 0
	s_and_b64 s[68:69], s[54:55], s[2:3]
.Lsx1_c:
	s_and_saveexec_b64 s[74:75], s[56:57]
	s_cbranch_execz .LBB0_432
	ds_read_b128 v[48:51], v174
	ds_read_b128 v[60:63], v192 offset:51456
	ds_read_b128 v[52:55], v174 offset:64
	ds_read_b128 v[64:67], v192 offset:51520
	ds_read_b128 v[56:59], v175 offset:5120
	ds_read_b128 v[68:71], v199
	ds_read_b128 v[72:75], v192 offset:60672
	ds_read_b128 v[76:79], v192 offset:60736
	ds_read_b128 v[80:83], v151
	ds_read_b128 v[84:87], v151 offset:16
	ds_read_b128 v[88:91], v151 offset:32
	ds_read_b128 v[92:95], v151 offset:48
	s_waitcnt lgkmcnt(10)
	v_mfma_f32_16x16x32_bf16 v[30:33], v[48:51], v[60:63], 0
	s_waitcnt lgkmcnt(8)
	v_mfma_f32_16x16x32_bf16 v[30:33], v[52:55], v[64:67], v[30:33]
	s_waitcnt lgkmcnt(6)
	v_mfma_f32_16x16x32_bf16 v[30:33], v[56:59], v[68:71], v[30:33]
	s_waitcnt lgkmcnt(5)
	v_mfma_f32_16x16x32_bf16 v[22:25], v[48:51], v[72:75], 0
	s_waitcnt lgkmcnt(4)
	v_mfma_f32_16x16x32_bf16 v[22:25], v[52:55], v[76:79], v[22:25]
	s_cmp_gt_u32 s36, 61
	s_cbranch_scc1 .Lis1bw
	s_add_i32 s24, s19, 0xffffffb0
	s_add_i32 s25, s21, 64
	s_and_b64 s[98:99], s[12:13], exec
	s_cselect_b32 s24, s25, s24
	v_lshl_add_u32 v194, s24, 6, v183
	v_lshlrev_b32_e32 v112, 1, v194
	global_load_dword v0, v112, s[44:45]
	global_load_dword v201, v112, s[44:45] offset:-1024
	global_load_dword v1, v112, s[42:43]
	global_load_dword v202, v112, s[42:43] offset:-1024
	global_load_dword v2, v112, s[0:1]
	global_load_dword v203, v112, s[0:1] offset:-1024
	global_load_dword v4, v112, s[76:77]
	global_load_dword v205, v112, s[76:77] offset:-1024
	global_load_dword v3, v112, s[34:35]
	global_load_dword v204, v112, s[34:35] offset:-1024
	v_add_u32_e32 v194, s24, v184
	v_lshlrev_b32_e32 v114, 2, v194
	global_load_dword v108, v114, s[40:41]
	global_load_dword v206, v114, s[40:41] offset:-32
	s_branch .Lis1b

.Lis1b:
	s_setprio 3
	v_lshrrev_b32_e32 v96, 6, v198
	v_mul_u32_u24_e32 v96, 0x500, v96
	v_mad_u32_u24 v96, v145, 20, v96
	v_and_b32_e32 v97, 15, v198
	v_lshl_add_u32 v96, v97, 1, v96
	v_add_u32_e32 v96, 0x10a00, v96
	s_waitcnt lgkmcnt(0)
	s_nop 1
	v_fmac_f32_dpp v30, v30, v80 row_newbcast:0 row_mask:0xf bank_mask:0xf
	v_fmac_f32_dpp v31, v31, v80 row_newbcast:0 row_mask:0xf bank_mask:0xf
	v_fmac_f32_dpp v32, v32, v80 row_newbcast:0 row_mask:0xf bank_mask:0xf
	v_fmac_f32_dpp v33, v33, v80 row_newbcast:0 row_mask:0xf bank_mask:0xf
	v_fmac_f32_dpp v30, v30, v81 row_newbcast:1 row_mask:0xf bank_mask:0xf
	v_fmac_f32_dpp v31, v31, v81 row_newbcast:1 row_mask:0xf bank_mask:0xf
	v_fmac_f32_dpp v32, v32, v81 row_newbcast:1 row_mask:0xf bank_mask:0xf
	v_fmac_f32_dpp v33, v33, v81 row_newbcast:1 row_mask:0xf bank_mask:0xf
	v_fmac_f32_dpp v30, v30, v82 row_newbcast:2 row_mask:0xf bank_mask:0xf
	v_fmac_f32_dpp v31, v31, v82 row_newbcast:2 row_mask:0xf bank_mask:0xf
	v_fmac_f32_dpp v32, v32, v82 row_newbcast:2 row_mask:0xf bank_mask:0xf
	v_fmac_f32_dpp v33, v33, v82 row_newbcast:2 row_mask:0xf bank_mask:0xf
	v_fmac_f32_dpp v30, v30, v83 row_newbcast:3 row_mask:0xf bank_mask:0xf
	v_fmac_f32_dpp v31, v31, v83 row_newbcast:3 row_mask:0xf bank_mask:0xf
	v_fmac_f32_dpp v32, v32, v83 row_newbcast:3 row_mask:0xf bank_mask:0xf
	v_fmac_f32_dpp v33, v33, v83 row_newbcast:3 row_mask:0xf bank_mask:0xf
	v_fmac_f32_dpp v30, v30, v84 row_newbcast:4 row_mask:0xf bank_mask:0xf
	v_fmac_f32_dpp v31, v31, v84 row_newbcast:4 row_mask:0xf bank_mask:0xf
	v_fmac_f32_dpp v32, v32, v84 row_newbcast:4 row_mask:0xf bank_mask:0xf
	v_fmac_f32_dpp v33, v33, v84 row_newbcast:4 row_mask:0xf bank_mask:0xf
	v_fmac_f32_dpp v30, v30, v85 row_newbcast:5 row_mask:0xf bank_mask:0xf
	v_fmac_f32_dpp v31, v31, v85 row_newbcast:5 row_mask:0xf bank_mask:0xf
	v_fmac_f32_dpp v32, v32, v85 row_newbcast:5 row_mask:0xf bank_mask:0xf
	v_fmac_f32_dpp v33, v33, v85 row_newbcast:5 row_mask:0xf bank_mask:0xf
	v_fmac_f32_dpp v30, v30, v86 row_newbcast:6 row_mask:0xf bank_mask:0xf
	v_fmac_f32_dpp v31, v31, v86 row_newbcast:6 row_mask:0xf bank_mask:0xf
	v_fmac_f32_dpp v32, v32, v86 row_newbcast:6 row_mask:0xf bank_mask:0xf
	v_fmac_f32_dpp v33, v33, v86 row_newbcast:6 row_mask:0xf bank_mask:0xf
	v_fmac_f32_dpp v30, v30, v87 row_newbcast:7 row_mask:0xf bank_mask:0xf
	v_fmac_f32_dpp v31, v31, v87 row_newbcast:7 row_mask:0xf bank_mask:0xf
	v_fmac_f32_dpp v32, v32, v87 row_newbcast:7 row_mask:0xf bank_mask:0xf
	v_fmac_f32_dpp v33, v33, v87 row_newbcast:7 row_mask:0xf bank_mask:0xf
	v_fmac_f32_dpp v30, v30, v88 row_newbcast:8 row_mask:0xf bank_mask:0xf
	v_fmac_f32_dpp v31, v31, v88 row_newbcast:8 row_mask:0xf bank_mask:0xf
	v_fmac_f32_dpp v32, v32, v88 row_newbcast:8 row_mask:0xf bank_mask:0xf
	v_fmac_f32_dpp v33, v33, v88 row_newbcast:8 row_mask:0xf bank_mask:0xf
	v_fmac_f32_dpp v30, v30, v89 row_newbcast:9 row_mask:0xf bank_mask:0xf
	v_fmac_f32_dpp v31, v31, v89 row_newbcast:9 row_mask:0xf bank_mask:0xf
	v_fmac_f32_dpp v32, v32, v89 row_newbcast:9 row_mask:0xf bank_mask:0xf
	v_fmac_f32_dpp v33, v33, v89 row_newbcast:9 row_mask:0xf bank_mask:0xf
	v_fmac_f32_dpp v30, v30, v90 row_newbcast:10 row_mask:0xf bank_mask:0xf
	v_fmac_f32_dpp v31, v31, v90 row_newbcast:10 row_mask:0xf bank_mask:0xf
	v_fmac_f32_dpp v32, v32, v90 row_newbcast:10 row_mask:0xf bank_mask:0xf
	v_fmac_f32_dpp v33, v33, v90 row_newbcast:10 row_mask:0xf bank_mask:0xf
	v_fmac_f32_dpp v30, v30, v91 row_newbcast:11 row_mask:0xf bank_mask:0xf
	v_fmac_f32_dpp v31, v31, v91 row_newbcast:11 row_mask:0xf bank_mask:0xf
	v_fmac_f32_dpp v32, v32, v91 row_newbcast:11 row_mask:0xf bank_mask:0xf
	v_fmac_f32_dpp v33, v33, v91 row_newbcast:11 row_mask:0xf bank_mask:0xf
	v_fmac_f32_dpp v30, v30, v92 row_newbcast:12 row_mask:0xf bank_mask:0xf
	v_fmac_f32_dpp v31, v31, v92 row_newbcast:12 row_mask:0xf bank_mask:0xf
	v_fmac_f32_dpp v32, v32, v92 row_newbcast:12 row_mask:0xf bank_mask:0xf
	v_fmac_f32_dpp v33, v33, v92 row_newbcast:12 row_mask:0xf bank_mask:0xf
	v_fmac_f32_dpp v30, v30, v93 row_newbcast:13 row_mask:0xf bank_mask:0xf
	v_fmac_f32_dpp v31, v31, v93 row_newbcast:13 row_mask:0xf bank_mask:0xf
	v_fmac_f32_dpp v32, v32, v93 row_newbcast:13 row_mask:0xf bank_mask:0xf
	v_fmac_f32_dpp v33, v33, v93 row_newbcast:13 row_mask:0xf bank_mask:0xf
	v_fmac_f32_dpp v30, v30, v94 row_newbcast:14 row_mask:0xf bank_mask:0xf
	v_fmac_f32_dpp v31, v31, v94 row_newbcast:14 row_mask:0xf bank_mask:0xf
	v_fmac_f32_dpp v32, v32, v94 row_newbcast:14 row_mask:0xf bank_mask:0xf
	v_fmac_f32_dpp v33, v33, v94 row_newbcast:14 row_mask:0xf bank_mask:0xf
	v_cvt_pk_bf16_f32 v80, v30, v31
	v_cvt_pk_bf16_f32 v81, v32, v33
	ds_write_b16 v96, v80 offset:5120
	ds_write_b16_d16_hi v96, v80 offset:5200
	ds_write_b16 v96, v81 offset:5280
	ds_write_b16_d16_hi v96, v81 offset:5360
	s_setprio 1

.Lpq1_end:
	s_waitcnt lgkmcnt(0)
	s_barrier
	s_and_b64 s[24:25], s[46:47], s[2:3]
	ds_read_b128 v[48:51], v180 offset:5120
	ds_read_b128 v[52:55], v170 offset:5120
	ds_read_b128 v[56:59], v170 offset:6400
	ds_read_b128 v[88:91], v242 offset:256
	ds_read_b128 v[92:95], v242 offset:320
	s_and_b64 s[98:99], s[56:57], exec
	s_cbranch_scc0 .Lcp1
	s_cmp_gt_u32 s36, 62
	s_cbranch_scc1 .Lcp1
	s_cmp_eq_u32 s36, 0
	s_cbranch_scc1 .Lvw1
	s_cmp_gt_u32 s36, 61
	s_cbranch_scc1 .Lvw1
	s_waitcnt vmcnt(13)
	s_branch .Lvx1

.Lsy1_m2:
	s_or_b64 exec, exec, s[74:75]
	s_nop 7
	s_nop 1
	s_and_saveexec_b64 s[74:75], s[56:57]
	s_cbranch_execz .Lsy1_w1
	ds_write_b128 v179, v[22:25] offset:4096
	s_add_i32 s98, s19, -32
	s_add_i32 s99, s21, 16
	s_bitcmp1_b32 s12, 0
	s_cselect_b32 s98, s99, s98
	v_cvt_pk_bf16_f32 v246, v22, v23
	v_cvt_pk_bf16_f32 v247, v24, v25
	v_lshl_add_u32 v245, s98, 7, v244
	global_store_dwordx2 v245, v[246:247], s[78:79]
